# EpiQ rope tiles: load each cos/sin table quad once per row step (kept in dead k-loop fragment registers) instead of twice
# speedup vs baseline: 1.0134x; 1.0134x over previous
.LBB0_829:
	v_lshl_add_u32 v156, s10, 8, v129
	v_readlane_b32 s10, v254, 14
	v_ashrrev_i32_e32 v157, 31, v156
	v_readlane_b32 s11, v254, 15
	s_cmp_gt_i32 s8, 7
	s_cselect_b64 s[52:53], -1, 0
	v_lshl_add_u64 v[158:159], v[156:157], 2, s[10:11]
	global_load_dword v190, v[158:159], off
	global_load_dword v191, v[158:159], off offset:64
	global_load_dword v192, v[158:159], off offset:128
	global_load_dword v193, v[158:159], off offset:192
	global_load_dword v194, v[158:159], off offset:512
	global_load_dword v195, v[158:159], off offset:576
	global_load_dword v196, v[158:159], off offset:640
	global_load_dword v197, v[158:159], off offset:704
	s_waitcnt vmcnt(0)
	v_mov_b32_e32 v160, v190
	s_lshl_b32 s25, s8, 8
	s_add_i32 s14, s25, s59
	s_mov_b64 s[10:11], -1
	v_lshlrev_b32_e32 v138, 1, v140
	s_cmp_lt_i32 s8, 8
	v_fmamk_f32 v160, v160, 0x3b000000, v167
	v_mul_f32_e32 v161, 0x4b800000, v160
	v_cmp_gt_f32_e32 vcc, s66, v160
	s_nop 1
	v_cndmask_b32_e32 v160, v160, v161, vcc
	v_rsq_f32_e32 v160, v160
	s_nop 0
	v_mul_f32_e32 v161, 0x45800000, v160
	v_cndmask_b32_e32 v160, v160, v161, vcc
	v_mul_f32_e32 v160, 0x3dd53b94, v160
	v_mov_b32_e32 v161, v160
	v_pk_mul_f32 v[162:163], v[124:125], v[160:161]
	v_pk_mul_f32 v[124:125], v[120:121], v[160:161]
	v_pk_mul_f32 v[120:121], v[116:117], v[160:161]
	v_pk_mul_f32 v[116:117], v[112:113], v[160:161]
	s_cbranch_scc1 .LBB0_831
	v_lshlrev_b64 v[112:113], 7, v[156:157]
	v_lshl_add_u64 v[176:177], v[146:147], 0, v[112:113]
	global_load_dwordx4 v[168:171], v[176:177], off
	v_lshl_add_u64 v[112:113], v[144:145], 0, v[112:113]
	global_load_dwordx4 v[172:175], v[112:113], off
	v_mov_b32_e32 v161, v160
	s_lshr_b32 s10, s14, 6
	v_mov_b64_e32 v[178:179], s[18:19]
	v_pk_mul_f32 v[182:183], v[122:123], v[160:161]
	v_pk_mul_f32 v[180:181], v[126:127], v[160:161]
	v_mad_i64_i32 v[178:179], s[8:9], v156, s67, v[178:179]
	s_mul_i32 s12, s10, 0xc0
	v_lshl_add_u64 v[178:179], s[12:13], 1, v[178:179]
	v_lshl_add_u64 v[178:179], v[178:179], 0, v[138:139]
	s_mov_b64 s[10:11], 0
	s_waitcnt vmcnt(1)
	v_mov_b64_e32 v[200:201], v[168:169]
	v_mov_b64_e32 v[202:203], v[170:171]
	v_pk_mul_f32 v[184:185], v[182:183], v[170:171]
	v_pk_mul_f32 v[186:187], v[124:125], v[168:169]
	v_pk_mul_f32 v[170:171], v[180:181], v[170:171]
	v_pk_mul_f32 v[168:169], v[162:163], v[168:169]
	s_waitcnt vmcnt(0)
	v_mov_b64_e32 v[204:205], v[172:173]
	v_mov_b64_e32 v[206:207], v[174:175]
	v_pk_fma_f32 v[180:181], v[180:181], v[174:175], v[184:185] neg_lo:[0,0,1] neg_hi:[0,0,1]
	v_pk_fma_f32 v[184:185], v[162:163], v[172:173], v[186:187] neg_lo:[0,0,1] neg_hi:[0,0,1]
	v_pk_fma_f32 v[170:171], v[182:183], v[174:175], v[170:171]
	v_pk_fma_f32 v[168:169], v[124:125], v[172:173], v[168:169]
	v_cvt_pk_bf16_f32 v172, v184, v185
	v_cvt_pk_bf16_f32 v173, v180, v181
	v_cvt_pk_bf16_f32 v168, v168, v169
	v_cvt_pk_bf16_f32 v169, v170, v171
	global_store_dwordx2 v[178:179], v[172:173], off offset:256
	global_store_dwordx2 v[178:179], v[168:169], off offset:320
	s_nop 1
	v_mov_b64_e32 v[168:169], v[200:201]
	v_mov_b64_e32 v[170:171], v[202:203]
	s_nop 0
	v_mov_b64_e32 v[172:173], v[204:205]
	v_mov_b64_e32 v[174:175], v[206:207]
	v_pk_mul_f32 v[176:177], v[114:115], v[160:161]
	v_pk_mul_f32 v[112:113], v[118:119], v[160:161]
	v_pk_mul_f32 v[180:181], v[176:177], v[170:171]
	v_pk_mul_f32 v[182:183], v[116:117], v[168:169]
	v_pk_mul_f32 v[170:171], v[112:113], v[170:171]
	v_pk_mul_f32 v[168:169], v[120:121], v[168:169]
	v_pk_fma_f32 v[112:113], v[112:113], v[174:175], v[180:181] neg_lo:[0,0,1] neg_hi:[0,0,1]
	v_pk_fma_f32 v[180:181], v[120:121], v[172:173], v[182:183] neg_lo:[0,0,1] neg_hi:[0,0,1]
	v_pk_fma_f32 v[170:171], v[176:177], v[174:175], v[170:171]
	v_pk_fma_f32 v[168:169], v[116:117], v[172:173], v[168:169]
	v_cvt_pk_bf16_f32 v172, v180, v181
	v_cvt_pk_bf16_f32 v173, v112, v113
	v_cvt_pk_bf16_f32 v112, v168, v169
	v_cvt_pk_bf16_f32 v113, v170, v171
	global_store_dwordx2 v[178:179], v[172:173], off offset:1024
	global_store_dwordx2 v[178:179], v[112:113], off offset:1088

.LBB0_833:
	s_nop 1
	v_mov_b32_e32 v113, v191
	s_nop 0
	v_cndmask_b32_e64 v116, 0, 1, s[52:53]
	v_cmp_ne_u32_e64 s[8:9], 1, v116
	v_or_b32_e32 v114, 16, v156
	s_mov_b64 s[54:55], -1
	s_andn2_b64 vcc, exec, s[52:53]
	v_fmamk_f32 v113, v113, 0x3b000000, v167
	v_mul_f32_e32 v115, 0x4b800000, v113
	v_cmp_gt_f32_e64 s[10:11], s66, v113
	s_nop 1
	v_cndmask_b32_e64 v113, v113, v115, s[10:11]
	v_rsq_f32_e32 v113, v113
	v_ashrrev_i32_e32 v115, 31, v114
	v_mul_f32_e32 v116, 0x45800000, v113
	v_cndmask_b32_e64 v113, v113, v116, s[10:11]
	v_mul_f32_e32 v116, 0x3dd53b94, v113
	v_mov_b32_e32 v117, v116
	v_pk_mul_f32 v[108:109], v[108:109], v[116:117]
	v_pk_mul_f32 v[104:105], v[104:105], v[116:117]
	v_pk_mul_f32 v[100:101], v[100:101], v[116:117]
	v_pk_mul_f32 v[96:97], v[96:97], v[116:117]
	s_cbranch_vccnz .LBB0_835
	v_lshlrev_b64 v[122:123], 7, v[114:115]
	v_lshl_add_u64 v[126:127], v[146:147], 0, v[122:123]
	global_load_dwordx4 v[118:121], v[126:127], off
	v_lshl_add_u64 v[160:161], v[144:145], 0, v[122:123]
	global_load_dwordx4 v[122:125], v[160:161], off
	v_mov_b32_e32 v117, v116
	s_lshr_b32 s12, s14, 6
	v_mov_b64_e32 v[162:163], s[18:19]
	v_pk_mul_f32 v[170:171], v[106:107], v[116:117]
	v_pk_mul_f32 v[168:169], v[110:111], v[116:117]
	v_mad_i64_i32 v[162:163], s[10:11], v114, s67, v[162:163]
	s_mulk_i32 s12, 0xc0
	v_lshl_add_u64 v[162:163], s[12:13], 1, v[162:163]
	v_lshl_add_u64 v[162:163], v[162:163], 0, v[138:139]
	s_mov_b64 s[54:55], 0
	s_waitcnt vmcnt(1)
	v_mov_b64_e32 v[200:201], v[118:119]
	v_mov_b64_e32 v[202:203], v[120:121]
	v_pk_mul_f32 v[172:173], v[170:171], v[120:121]
	v_pk_mul_f32 v[174:175], v[104:105], v[118:119]
	v_pk_mul_f32 v[120:121], v[168:169], v[120:121]
	v_pk_mul_f32 v[118:119], v[108:109], v[118:119]
	s_waitcnt vmcnt(0)
	v_mov_b64_e32 v[204:205], v[122:123]
	v_mov_b64_e32 v[206:207], v[124:125]
	v_pk_fma_f32 v[168:169], v[168:169], v[124:125], v[172:173] neg_lo:[0,0,1] neg_hi:[0,0,1]
	v_pk_fma_f32 v[172:173], v[108:109], v[122:123], v[174:175] neg_lo:[0,0,1] neg_hi:[0,0,1]
	v_pk_fma_f32 v[120:121], v[170:171], v[124:125], v[120:121]
	v_pk_fma_f32 v[118:119], v[104:105], v[122:123], v[118:119]
	v_cvt_pk_bf16_f32 v122, v172, v173
	v_cvt_pk_bf16_f32 v123, v168, v169
	v_cvt_pk_bf16_f32 v118, v118, v119
	v_cvt_pk_bf16_f32 v119, v120, v121
	global_store_dwordx2 v[162:163], v[122:123], off offset:256
	global_store_dwordx2 v[162:163], v[118:119], off offset:320
	s_nop 1
	v_mov_b64_e32 v[118:119], v[200:201]
	v_mov_b64_e32 v[120:121], v[202:203]
	s_nop 0
	v_mov_b64_e32 v[122:123], v[204:205]
	v_mov_b64_e32 v[124:125], v[206:207]
	v_pk_mul_f32 v[160:161], v[98:99], v[116:117]
	v_pk_mul_f32 v[126:127], v[102:103], v[116:117]
	v_pk_mul_f32 v[168:169], v[160:161], v[120:121]
	v_pk_mul_f32 v[170:171], v[96:97], v[118:119]
	v_pk_mul_f32 v[120:121], v[126:127], v[120:121]
	v_pk_mul_f32 v[118:119], v[100:101], v[118:119]
	v_pk_fma_f32 v[126:127], v[126:127], v[124:125], v[168:169] neg_lo:[0,0,1] neg_hi:[0,0,1]
	v_pk_fma_f32 v[168:169], v[100:101], v[122:123], v[170:171] neg_lo:[0,0,1] neg_hi:[0,0,1]
	v_pk_fma_f32 v[120:121], v[160:161], v[124:125], v[120:121]
	v_pk_fma_f32 v[118:119], v[96:97], v[122:123], v[118:119]
	v_cvt_pk_bf16_f32 v122, v168, v169
	v_cvt_pk_bf16_f32 v123, v126, v127
	v_cvt_pk_bf16_f32 v118, v118, v119
	v_cvt_pk_bf16_f32 v119, v120, v121
	global_store_dwordx2 v[162:163], v[122:123], off offset:1024
	global_store_dwordx2 v[162:163], v[118:119], off offset:1088

.LBB0_837:
	s_nop 1
	v_mov_b32_e32 v97, v192
	v_or_b32_e32 v96, 32, v156
	s_mov_b64 s[52:53], -1
	s_and_b64 vcc, exec, s[8:9]
	v_fmamk_f32 v97, v97, 0x3b000000, v167
	v_mul_f32_e32 v98, 0x4b800000, v97
	v_cmp_gt_f32_e64 s[10:11], s66, v97
	s_nop 1
	v_cndmask_b32_e64 v97, v97, v98, s[10:11]
	v_rsq_f32_e32 v98, v97
	v_ashrrev_i32_e32 v97, 31, v96
	v_mul_f32_e32 v99, 0x45800000, v98
	v_cndmask_b32_e64 v98, v98, v99, s[10:11]
	v_mul_f32_e32 v98, 0x3dd53b94, v98
	v_mov_b32_e32 v99, v98
	v_pk_mul_f32 v[92:93], v[92:93], v[98:99]
	v_pk_mul_f32 v[88:89], v[88:89], v[98:99]
	v_pk_mul_f32 v[84:85], v[84:85], v[98:99]
	v_pk_mul_f32 v[80:81], v[80:81], v[98:99]
	s_cbranch_vccnz .LBB0_839
	v_lshlrev_b64 v[104:105], 7, v[96:97]
	v_lshl_add_u64 v[108:109], v[146:147], 0, v[104:105]
	global_load_dwordx4 v[100:103], v[108:109], off
	v_lshl_add_u64 v[110:111], v[144:145], 0, v[104:105]
	global_load_dwordx4 v[104:107], v[110:111], off
	v_mov_b32_e32 v99, v98
	s_lshr_b32 s12, s14, 6
	v_mov_b64_e32 v[114:115], s[18:19]
	v_pk_mul_f32 v[118:119], v[90:91], v[98:99]
	v_pk_mul_f32 v[116:117], v[94:95], v[98:99]
	v_mad_i64_i32 v[114:115], s[10:11], v96, s67, v[114:115]
	s_mulk_i32 s12, 0xc0
	v_lshl_add_u64 v[114:115], s[12:13], 1, v[114:115]
	v_lshl_add_u64 v[114:115], v[114:115], 0, v[138:139]
	s_mov_b64 s[52:53], 0
	s_waitcnt vmcnt(1)
	v_mov_b64_e32 v[200:201], v[100:101]
	v_mov_b64_e32 v[202:203], v[102:103]
	v_pk_mul_f32 v[120:121], v[118:119], v[102:103]
	v_pk_mul_f32 v[122:123], v[88:89], v[100:101]
	v_pk_mul_f32 v[102:103], v[116:117], v[102:103]
	v_pk_mul_f32 v[100:101], v[92:93], v[100:101]
	s_waitcnt vmcnt(0)
	v_mov_b64_e32 v[204:205], v[104:105]
	v_mov_b64_e32 v[206:207], v[106:107]
	v_pk_fma_f32 v[116:117], v[116:117], v[106:107], v[120:121] neg_lo:[0,0,1] neg_hi:[0,0,1]
	v_pk_fma_f32 v[120:121], v[92:93], v[104:105], v[122:123] neg_lo:[0,0,1] neg_hi:[0,0,1]
	v_pk_fma_f32 v[102:103], v[118:119], v[106:107], v[102:103]
	v_pk_fma_f32 v[100:101], v[88:89], v[104:105], v[100:101]
	v_cvt_pk_bf16_f32 v104, v120, v121
	v_cvt_pk_bf16_f32 v105, v116, v117
	v_cvt_pk_bf16_f32 v100, v100, v101
	v_cvt_pk_bf16_f32 v101, v102, v103
	global_store_dwordx2 v[114:115], v[104:105], off offset:256
	global_store_dwordx2 v[114:115], v[100:101], off offset:320
	s_nop 1
	v_mov_b64_e32 v[100:101], v[200:201]
	v_mov_b64_e32 v[102:103], v[202:203]
	s_nop 0
	v_mov_b64_e32 v[104:105], v[204:205]
	v_mov_b64_e32 v[106:107], v[206:207]
	v_pk_mul_f32 v[110:111], v[82:83], v[98:99]
	v_pk_mul_f32 v[108:109], v[86:87], v[98:99]
	v_pk_mul_f32 v[116:117], v[110:111], v[102:103]
	v_pk_mul_f32 v[118:119], v[80:81], v[100:101]
	v_pk_mul_f32 v[102:103], v[108:109], v[102:103]
	v_pk_mul_f32 v[100:101], v[84:85], v[100:101]
	v_pk_fma_f32 v[108:109], v[108:109], v[106:107], v[116:117] neg_lo:[0,0,1] neg_hi:[0,0,1]
	v_pk_fma_f32 v[116:117], v[84:85], v[104:105], v[118:119] neg_lo:[0,0,1] neg_hi:[0,0,1]
	v_pk_fma_f32 v[102:103], v[110:111], v[106:107], v[102:103]
	v_pk_fma_f32 v[100:101], v[80:81], v[104:105], v[100:101]
	v_cvt_pk_bf16_f32 v104, v116, v117
	v_cvt_pk_bf16_f32 v105, v108, v109
	v_cvt_pk_bf16_f32 v100, v100, v101
	v_cvt_pk_bf16_f32 v101, v102, v103
	global_store_dwordx2 v[114:115], v[104:105], off offset:1024
	global_store_dwordx2 v[114:115], v[100:101], off offset:1088

.LBB0_841:
	s_nop 1
	v_mov_b32_e32 v81, v193
	v_or_b32_e32 v80, 48, v156
	s_mov_b64 s[52:53], -1
	s_and_b64 vcc, exec, s[8:9]
	v_fmamk_f32 v81, v81, 0x3b000000, v167
	v_mul_f32_e32 v82, 0x4b800000, v81
	v_cmp_gt_f32_e64 s[10:11], s66, v81
	s_nop 1
	v_cndmask_b32_e64 v81, v81, v82, s[10:11]
	v_rsq_f32_e32 v82, v81
	v_ashrrev_i32_e32 v81, 31, v80
	v_mul_f32_e32 v83, 0x45800000, v82
	v_cndmask_b32_e64 v82, v82, v83, s[10:11]
	v_mul_f32_e32 v82, 0x3dd53b94, v82
	v_mov_b32_e32 v83, v82
	v_pk_mul_f32 v[76:77], v[76:77], v[82:83]
	v_pk_mul_f32 v[72:73], v[72:73], v[82:83]
	v_pk_mul_f32 v[68:69], v[68:69], v[82:83]
	v_pk_mul_f32 v[64:65], v[64:65], v[82:83]
	s_cbranch_vccnz .LBB0_843
	v_lshlrev_b64 v[88:89], 7, v[80:81]
	v_lshl_add_u64 v[92:93], v[146:147], 0, v[88:89]
	global_load_dwordx4 v[84:87], v[92:93], off
	v_lshl_add_u64 v[94:95], v[144:145], 0, v[88:89]
	global_load_dwordx4 v[88:91], v[94:95], off
	v_mov_b32_e32 v83, v82
	s_lshr_b32 s12, s14, 6
	v_mov_b64_e32 v[96:97], s[18:19]
	v_pk_mul_f32 v[100:101], v[74:75], v[82:83]
	v_pk_mul_f32 v[98:99], v[78:79], v[82:83]
	v_mad_i64_i32 v[96:97], s[10:11], v80, s67, v[96:97]
	s_mulk_i32 s12, 0xc0
	v_lshl_add_u64 v[96:97], s[12:13], 1, v[96:97]
	v_lshl_add_u64 v[96:97], v[96:97], 0, v[138:139]
	s_mov_b64 s[52:53], 0
	s_waitcnt vmcnt(1)
	v_mov_b64_e32 v[200:201], v[84:85]
	v_mov_b64_e32 v[202:203], v[86:87]
	v_pk_mul_f32 v[102:103], v[100:101], v[86:87]
	v_pk_mul_f32 v[104:105], v[72:73], v[84:85]
	v_pk_mul_f32 v[86:87], v[98:99], v[86:87]
	v_pk_mul_f32 v[84:85], v[76:77], v[84:85]
	s_waitcnt vmcnt(0)
	v_mov_b64_e32 v[204:205], v[88:89]
	v_mov_b64_e32 v[206:207], v[90:91]
	v_pk_fma_f32 v[98:99], v[98:99], v[90:91], v[102:103] neg_lo:[0,0,1] neg_hi:[0,0,1]
	v_pk_fma_f32 v[102:103], v[76:77], v[88:89], v[104:105] neg_lo:[0,0,1] neg_hi:[0,0,1]
	v_pk_fma_f32 v[86:87], v[100:101], v[90:91], v[86:87]
	v_pk_fma_f32 v[84:85], v[72:73], v[88:89], v[84:85]
	v_cvt_pk_bf16_f32 v88, v102, v103
	v_cvt_pk_bf16_f32 v89, v98, v99
	v_cvt_pk_bf16_f32 v84, v84, v85
	v_cvt_pk_bf16_f32 v85, v86, v87
	global_store_dwordx2 v[96:97], v[88:89], off offset:256
	global_store_dwordx2 v[96:97], v[84:85], off offset:320
	s_nop 1
	v_mov_b64_e32 v[84:85], v[200:201]
	v_mov_b64_e32 v[86:87], v[202:203]
	s_nop 0
	v_mov_b64_e32 v[88:89], v[204:205]
	v_mov_b64_e32 v[90:91], v[206:207]
	v_pk_mul_f32 v[94:95], v[66:67], v[82:83]
	v_pk_mul_f32 v[92:93], v[70:71], v[82:83]
	v_pk_mul_f32 v[98:99], v[94:95], v[86:87]
	v_pk_mul_f32 v[100:101], v[64:65], v[84:85]
	v_pk_mul_f32 v[86:87], v[92:93], v[86:87]
	v_pk_mul_f32 v[84:85], v[68:69], v[84:85]
	v_pk_fma_f32 v[92:93], v[92:93], v[90:91], v[98:99] neg_lo:[0,0,1] neg_hi:[0,0,1]
	v_pk_fma_f32 v[98:99], v[68:69], v[88:89], v[100:101] neg_lo:[0,0,1] neg_hi:[0,0,1]
	v_pk_fma_f32 v[86:87], v[94:95], v[90:91], v[86:87]
	v_pk_fma_f32 v[84:85], v[64:65], v[88:89], v[84:85]
	v_cvt_pk_bf16_f32 v88, v98, v99
	v_cvt_pk_bf16_f32 v89, v92, v93
	v_cvt_pk_bf16_f32 v84, v84, v85
	v_cvt_pk_bf16_f32 v85, v86, v87
	global_store_dwordx2 v[96:97], v[88:89], off offset:1024
	global_store_dwordx2 v[96:97], v[84:85], off offset:1088

.LBB0_845:
	s_nop 1
	v_mov_b32_e32 v65, v194
	v_add_u32_e32 v64, 0x80, v156
	s_mov_b64 s[52:53], -1
	s_and_b64 vcc, exec, s[8:9]
	v_fmamk_f32 v65, v65, 0x3b000000, v167
	v_mul_f32_e32 v66, 0x4b800000, v65
	v_cmp_gt_f32_e64 s[10:11], s66, v65
	s_nop 1
	v_cndmask_b32_e64 v65, v65, v66, s[10:11]
	v_rsq_f32_e32 v66, v65
	v_ashrrev_i32_e32 v65, 31, v64
	v_mul_f32_e32 v67, 0x45800000, v66
	v_cndmask_b32_e64 v66, v66, v67, s[10:11]
	v_mul_f32_e32 v66, 0x3dd53b94, v66
	v_mov_b32_e32 v67, v66
	v_pk_mul_f32 v[60:61], v[60:61], v[66:67]
	v_pk_mul_f32 v[56:57], v[56:57], v[66:67]
	v_pk_mul_f32 v[52:53], v[52:53], v[66:67]
	v_pk_mul_f32 v[48:49], v[48:49], v[66:67]
	s_cbranch_vccnz .LBB0_847
	v_lshlrev_b64 v[72:73], 7, v[64:65]
	v_lshl_add_u64 v[76:77], v[146:147], 0, v[72:73]
	global_load_dwordx4 v[68:71], v[76:77], off
	v_lshl_add_u64 v[78:79], v[144:145], 0, v[72:73]
	global_load_dwordx4 v[72:75], v[78:79], off
	v_mov_b32_e32 v67, v66
	s_lshr_b32 s12, s14, 6
	v_mov_b64_e32 v[80:81], s[18:19]
	v_pk_mul_f32 v[84:85], v[58:59], v[66:67]
	v_pk_mul_f32 v[82:83], v[62:63], v[66:67]
	v_mad_i64_i32 v[80:81], s[10:11], v64, s67, v[80:81]
	s_mulk_i32 s12, 0xc0
	v_lshl_add_u64 v[80:81], s[12:13], 1, v[80:81]
	v_lshl_add_u64 v[80:81], v[80:81], 0, v[138:139]
	s_mov_b64 s[52:53], 0
	s_waitcnt vmcnt(1)
	v_mov_b64_e32 v[200:201], v[68:69]
	v_mov_b64_e32 v[202:203], v[70:71]
	v_pk_mul_f32 v[86:87], v[84:85], v[70:71]
	v_pk_mul_f32 v[88:89], v[56:57], v[68:69]
	v_pk_mul_f32 v[70:71], v[82:83], v[70:71]
	v_pk_mul_f32 v[68:69], v[60:61], v[68:69]
	s_waitcnt vmcnt(0)
	v_mov_b64_e32 v[204:205], v[72:73]
	v_mov_b64_e32 v[206:207], v[74:75]
	v_pk_fma_f32 v[82:83], v[82:83], v[74:75], v[86:87] neg_lo:[0,0,1] neg_hi:[0,0,1]
	v_pk_fma_f32 v[86:87], v[60:61], v[72:73], v[88:89] neg_lo:[0,0,1] neg_hi:[0,0,1]
	v_pk_fma_f32 v[70:71], v[84:85], v[74:75], v[70:71]
	v_pk_fma_f32 v[68:69], v[56:57], v[72:73], v[68:69]
	v_cvt_pk_bf16_f32 v72, v86, v87
	v_cvt_pk_bf16_f32 v73, v82, v83
	v_cvt_pk_bf16_f32 v68, v68, v69
	v_cvt_pk_bf16_f32 v69, v70, v71
	global_store_dwordx2 v[80:81], v[72:73], off offset:256
	global_store_dwordx2 v[80:81], v[68:69], off offset:320
	s_nop 1
	v_mov_b64_e32 v[68:69], v[200:201]
	v_mov_b64_e32 v[70:71], v[202:203]
	s_nop 0
	v_mov_b64_e32 v[72:73], v[204:205]
	v_mov_b64_e32 v[74:75], v[206:207]
	v_pk_mul_f32 v[78:79], v[50:51], v[66:67]
	v_pk_mul_f32 v[76:77], v[54:55], v[66:67]
	v_pk_mul_f32 v[82:83], v[78:79], v[70:71]
	v_pk_mul_f32 v[84:85], v[48:49], v[68:69]
	v_pk_mul_f32 v[70:71], v[76:77], v[70:71]
	v_pk_mul_f32 v[68:69], v[52:53], v[68:69]
	v_pk_fma_f32 v[76:77], v[76:77], v[74:75], v[82:83] neg_lo:[0,0,1] neg_hi:[0,0,1]
	v_pk_fma_f32 v[82:83], v[52:53], v[72:73], v[84:85] neg_lo:[0,0,1] neg_hi:[0,0,1]
	v_pk_fma_f32 v[70:71], v[78:79], v[74:75], v[70:71]
	v_pk_fma_f32 v[68:69], v[48:49], v[72:73], v[68:69]
	v_cvt_pk_bf16_f32 v72, v82, v83
	v_cvt_pk_bf16_f32 v73, v76, v77
	v_cvt_pk_bf16_f32 v68, v68, v69
	v_cvt_pk_bf16_f32 v69, v70, v71
	global_store_dwordx2 v[80:81], v[72:73], off offset:1024
	global_store_dwordx2 v[80:81], v[68:69], off offset:1088

.LBB0_849:
	s_nop 1
	v_mov_b32_e32 v49, v195
	v_add_u32_e32 v48, 0x90, v156
	s_mov_b64 s[52:53], -1
	s_and_b64 vcc, exec, s[8:9]
	v_fmamk_f32 v49, v49, 0x3b000000, v167
	v_mul_f32_e32 v50, 0x4b800000, v49
	v_cmp_gt_f32_e64 s[10:11], s66, v49
	s_nop 1
	v_cndmask_b32_e64 v49, v49, v50, s[10:11]
	v_rsq_f32_e32 v50, v49
	v_ashrrev_i32_e32 v49, 31, v48
	v_mul_f32_e32 v51, 0x45800000, v50
	v_cndmask_b32_e64 v50, v50, v51, s[10:11]
	v_mul_f32_e32 v50, 0x3dd53b94, v50
	v_mov_b32_e32 v51, v50
	v_pk_mul_f32 v[44:45], v[44:45], v[50:51]
	v_pk_mul_f32 v[40:41], v[40:41], v[50:51]
	v_pk_mul_f32 v[36:37], v[36:37], v[50:51]
	v_pk_mul_f32 v[32:33], v[32:33], v[50:51]
	s_cbranch_vccnz .LBB0_851
	v_lshlrev_b64 v[56:57], 7, v[48:49]
	v_lshl_add_u64 v[60:61], v[146:147], 0, v[56:57]
	global_load_dwordx4 v[52:55], v[60:61], off
	v_lshl_add_u64 v[62:63], v[144:145], 0, v[56:57]
	global_load_dwordx4 v[56:59], v[62:63], off
	v_mov_b32_e32 v51, v50
	s_lshr_b32 s12, s14, 6
	v_mov_b64_e32 v[64:65], s[18:19]
	v_pk_mul_f32 v[68:69], v[42:43], v[50:51]
	v_pk_mul_f32 v[66:67], v[46:47], v[50:51]
	v_mad_i64_i32 v[64:65], s[10:11], v48, s67, v[64:65]
	s_mulk_i32 s12, 0xc0
	v_lshl_add_u64 v[64:65], s[12:13], 1, v[64:65]
	v_lshl_add_u64 v[64:65], v[64:65], 0, v[138:139]
	s_mov_b64 s[52:53], 0
	s_waitcnt vmcnt(1)
	v_mov_b64_e32 v[200:201], v[52:53]
	v_mov_b64_e32 v[202:203], v[54:55]
	v_pk_mul_f32 v[70:71], v[68:69], v[54:55]
	v_pk_mul_f32 v[72:73], v[40:41], v[52:53]
	v_pk_mul_f32 v[54:55], v[66:67], v[54:55]
	v_pk_mul_f32 v[52:53], v[44:45], v[52:53]
	s_waitcnt vmcnt(0)
	v_mov_b64_e32 v[204:205], v[56:57]
	v_mov_b64_e32 v[206:207], v[58:59]
	v_pk_fma_f32 v[66:67], v[66:67], v[58:59], v[70:71] neg_lo:[0,0,1] neg_hi:[0,0,1]
	v_pk_fma_f32 v[70:71], v[44:45], v[56:57], v[72:73] neg_lo:[0,0,1] neg_hi:[0,0,1]
	v_pk_fma_f32 v[54:55], v[68:69], v[58:59], v[54:55]
	v_pk_fma_f32 v[52:53], v[40:41], v[56:57], v[52:53]
	v_cvt_pk_bf16_f32 v56, v70, v71
	v_cvt_pk_bf16_f32 v57, v66, v67
	v_cvt_pk_bf16_f32 v52, v52, v53
	v_cvt_pk_bf16_f32 v53, v54, v55
	global_store_dwordx2 v[64:65], v[56:57], off offset:256
	global_store_dwordx2 v[64:65], v[52:53], off offset:320
	s_nop 1
	v_mov_b64_e32 v[52:53], v[200:201]
	v_mov_b64_e32 v[54:55], v[202:203]
	s_nop 0
	v_mov_b64_e32 v[56:57], v[204:205]
	v_mov_b64_e32 v[58:59], v[206:207]
	v_pk_mul_f32 v[62:63], v[34:35], v[50:51]
	v_pk_mul_f32 v[60:61], v[38:39], v[50:51]
	v_pk_mul_f32 v[66:67], v[62:63], v[54:55]
	v_pk_mul_f32 v[68:69], v[32:33], v[52:53]
	v_pk_mul_f32 v[54:55], v[60:61], v[54:55]
	v_pk_mul_f32 v[52:53], v[36:37], v[52:53]
	v_pk_fma_f32 v[60:61], v[60:61], v[58:59], v[66:67] neg_lo:[0,0,1] neg_hi:[0,0,1]
	v_pk_fma_f32 v[66:67], v[36:37], v[56:57], v[68:69] neg_lo:[0,0,1] neg_hi:[0,0,1]
	v_pk_fma_f32 v[54:55], v[62:63], v[58:59], v[54:55]
	v_pk_fma_f32 v[52:53], v[32:33], v[56:57], v[52:53]
	v_cvt_pk_bf16_f32 v56, v66, v67
	v_cvt_pk_bf16_f32 v57, v60, v61
	v_cvt_pk_bf16_f32 v52, v52, v53
	v_cvt_pk_bf16_f32 v53, v54, v55
	global_store_dwordx2 v[64:65], v[56:57], off offset:1024
	global_store_dwordx2 v[64:65], v[52:53], off offset:1088

.LBB0_853:
	s_nop 1
	v_mov_b32_e32 v33, v196
	v_add_u32_e32 v32, 0xa0, v156
	s_mov_b64 s[52:53], -1
	s_and_b64 vcc, exec, s[8:9]
	v_fmamk_f32 v33, v33, 0x3b000000, v167
	v_mul_f32_e32 v34, 0x4b800000, v33
	v_cmp_gt_f32_e64 s[10:11], s66, v33
	s_nop 1
	v_cndmask_b32_e64 v33, v33, v34, s[10:11]
	v_rsq_f32_e32 v34, v33
	v_ashrrev_i32_e32 v33, 31, v32
	v_mul_f32_e32 v35, 0x45800000, v34
	v_cndmask_b32_e64 v34, v34, v35, s[10:11]
	v_mul_f32_e32 v34, 0x3dd53b94, v34
	v_mov_b32_e32 v35, v34
	v_pk_mul_f32 v[28:29], v[28:29], v[34:35]
	v_pk_mul_f32 v[24:25], v[24:25], v[34:35]
	v_pk_mul_f32 v[20:21], v[20:21], v[34:35]
	v_pk_mul_f32 v[16:17], v[16:17], v[34:35]
	s_cbranch_vccnz .LBB0_855
	v_lshlrev_b64 v[40:41], 7, v[32:33]
	v_lshl_add_u64 v[44:45], v[146:147], 0, v[40:41]
	global_load_dwordx4 v[36:39], v[44:45], off
	v_lshl_add_u64 v[46:47], v[144:145], 0, v[40:41]
	global_load_dwordx4 v[40:43], v[46:47], off
	v_mov_b32_e32 v35, v34
	s_lshr_b32 s12, s14, 6
	v_mov_b64_e32 v[48:49], s[18:19]
	v_pk_mul_f32 v[52:53], v[26:27], v[34:35]
	v_pk_mul_f32 v[50:51], v[30:31], v[34:35]
	v_mad_i64_i32 v[48:49], s[10:11], v32, s67, v[48:49]
	s_mulk_i32 s12, 0xc0
	v_lshl_add_u64 v[48:49], s[12:13], 1, v[48:49]
	v_lshl_add_u64 v[48:49], v[48:49], 0, v[138:139]
	s_mov_b64 s[52:53], 0
	s_waitcnt vmcnt(1)
	v_mov_b64_e32 v[200:201], v[36:37]
	v_mov_b64_e32 v[202:203], v[38:39]
	v_pk_mul_f32 v[54:55], v[52:53], v[38:39]
	v_pk_mul_f32 v[56:57], v[24:25], v[36:37]
	v_pk_mul_f32 v[38:39], v[50:51], v[38:39]
	v_pk_mul_f32 v[36:37], v[28:29], v[36:37]
	s_waitcnt vmcnt(0)
	v_mov_b64_e32 v[204:205], v[40:41]
	v_mov_b64_e32 v[206:207], v[42:43]
	v_pk_fma_f32 v[50:51], v[50:51], v[42:43], v[54:55] neg_lo:[0,0,1] neg_hi:[0,0,1]
	v_pk_fma_f32 v[54:55], v[28:29], v[40:41], v[56:57] neg_lo:[0,0,1] neg_hi:[0,0,1]
	v_pk_fma_f32 v[38:39], v[52:53], v[42:43], v[38:39]
	v_pk_fma_f32 v[36:37], v[24:25], v[40:41], v[36:37]
	v_cvt_pk_bf16_f32 v40, v54, v55
	v_cvt_pk_bf16_f32 v41, v50, v51
	v_cvt_pk_bf16_f32 v36, v36, v37
	v_cvt_pk_bf16_f32 v37, v38, v39
	global_store_dwordx2 v[48:49], v[40:41], off offset:256
	global_store_dwordx2 v[48:49], v[36:37], off offset:320
	s_nop 1
	v_mov_b64_e32 v[36:37], v[200:201]
	v_mov_b64_e32 v[38:39], v[202:203]
	s_nop 0
	v_mov_b64_e32 v[40:41], v[204:205]
	v_mov_b64_e32 v[42:43], v[206:207]
	v_pk_mul_f32 v[46:47], v[18:19], v[34:35]
	v_pk_mul_f32 v[44:45], v[22:23], v[34:35]
	v_pk_mul_f32 v[50:51], v[46:47], v[38:39]
	v_pk_mul_f32 v[52:53], v[16:17], v[36:37]
	v_pk_mul_f32 v[38:39], v[44:45], v[38:39]
	v_pk_mul_f32 v[36:37], v[20:21], v[36:37]
	v_pk_fma_f32 v[44:45], v[44:45], v[42:43], v[50:51] neg_lo:[0,0,1] neg_hi:[0,0,1]
	v_pk_fma_f32 v[50:51], v[20:21], v[40:41], v[52:53] neg_lo:[0,0,1] neg_hi:[0,0,1]
	v_pk_fma_f32 v[38:39], v[46:47], v[42:43], v[38:39]
	v_pk_fma_f32 v[36:37], v[16:17], v[40:41], v[36:37]
	v_cvt_pk_bf16_f32 v40, v50, v51
	v_cvt_pk_bf16_f32 v41, v44, v45
	v_cvt_pk_bf16_f32 v36, v36, v37
	v_cvt_pk_bf16_f32 v37, v38, v39
	global_store_dwordx2 v[48:49], v[40:41], off offset:1024
	global_store_dwordx2 v[48:49], v[36:37], off offset:1088

.LBB0_857:
	s_nop 1
	v_mov_b32_e32 v17, v197
	v_add_u32_e32 v16, 0xb0, v156
	s_mov_b64 s[52:53], -1
	s_and_b64 vcc, exec, s[8:9]
	v_fmamk_f32 v17, v17, 0x3b000000, v167
	v_mul_f32_e32 v18, 0x4b800000, v17
	v_cmp_gt_f32_e64 s[10:11], s66, v17
	s_nop 1
	v_cndmask_b32_e64 v17, v17, v18, s[10:11]
	v_rsq_f32_e32 v18, v17
	v_ashrrev_i32_e32 v17, 31, v16
	v_mul_f32_e32 v19, 0x45800000, v18
	v_cndmask_b32_e64 v18, v18, v19, s[10:11]
	v_mul_f32_e32 v18, 0x3dd53b94, v18
	v_mov_b32_e32 v19, v18
	v_pk_mul_f32 v[12:13], v[12:13], v[18:19]
	v_pk_mul_f32 v[8:9], v[8:9], v[18:19]
	v_pk_mul_f32 v[4:5], v[4:5], v[18:19]
	v_pk_mul_f32 v[0:1], v[0:1], v[18:19]
	s_cbranch_vccnz .LBB0_860
	v_lshlrev_b64 v[24:25], 7, v[16:17]
	v_lshl_add_u64 v[28:29], v[146:147], 0, v[24:25]
	global_load_dwordx4 v[20:23], v[28:29], off
	v_lshl_add_u64 v[30:31], v[144:145], 0, v[24:25]
	global_load_dwordx4 v[24:27], v[30:31], off
	v_mov_b32_e32 v19, v18
	s_lshr_b32 s10, s14, 6
	v_mov_b64_e32 v[32:33], s[18:19]
	v_pk_mul_f32 v[36:37], v[10:11], v[18:19]
	v_pk_mul_f32 v[34:35], v[14:15], v[18:19]
	v_mad_i64_i32 v[32:33], s[8:9], v16, s67, v[32:33]
	s_mul_i32 s12, s10, 0xc0
	v_lshl_add_u64 v[32:33], s[12:13], 1, v[32:33]
	v_lshl_add_u64 v[32:33], v[32:33], 0, v[138:139]
	s_waitcnt vmcnt(1)
	v_mov_b64_e32 v[200:201], v[20:21]
	v_mov_b64_e32 v[202:203], v[22:23]
	v_pk_mul_f32 v[38:39], v[36:37], v[22:23]
	v_pk_mul_f32 v[40:41], v[8:9], v[20:21]
	v_pk_mul_f32 v[22:23], v[34:35], v[22:23]
	v_pk_mul_f32 v[20:21], v[12:13], v[20:21]
	s_waitcnt vmcnt(0)
	v_mov_b64_e32 v[204:205], v[24:25]
	v_mov_b64_e32 v[206:207], v[26:27]
	v_pk_fma_f32 v[34:35], v[34:35], v[26:27], v[38:39] neg_lo:[0,0,1] neg_hi:[0,0,1]
	v_pk_fma_f32 v[38:39], v[12:13], v[24:25], v[40:41] neg_lo:[0,0,1] neg_hi:[0,0,1]
	v_pk_fma_f32 v[22:23], v[36:37], v[26:27], v[22:23]
	v_pk_fma_f32 v[20:21], v[8:9], v[24:25], v[20:21]
	v_cvt_pk_bf16_f32 v24, v38, v39
	v_cvt_pk_bf16_f32 v25, v34, v35
	v_cvt_pk_bf16_f32 v20, v20, v21
	v_cvt_pk_bf16_f32 v21, v22, v23
	global_store_dwordx2 v[32:33], v[24:25], off offset:256
	global_store_dwordx2 v[32:33], v[20:21], off offset:320
	s_nop 1
	v_mov_b64_e32 v[20:21], v[200:201]
	v_mov_b64_e32 v[22:23], v[202:203]
	s_nop 0
	v_mov_b64_e32 v[24:25], v[204:205]
	v_mov_b64_e32 v[26:27], v[206:207]
	v_pk_mul_f32 v[30:31], v[2:3], v[18:19]
	v_pk_mul_f32 v[28:29], v[6:7], v[18:19]
	v_pk_mul_f32 v[34:35], v[30:31], v[22:23]
	v_pk_mul_f32 v[36:37], v[0:1], v[20:21]
	v_pk_mul_f32 v[22:23], v[28:29], v[22:23]
	v_pk_mul_f32 v[20:21], v[4:5], v[20:21]
	v_pk_fma_f32 v[28:29], v[28:29], v[26:27], v[34:35] neg_lo:[0,0,1] neg_hi:[0,0,1]
	v_pk_fma_f32 v[34:35], v[4:5], v[24:25], v[36:37] neg_lo:[0,0,1] neg_hi:[0,0,1]
	v_pk_fma_f32 v[22:23], v[30:31], v[26:27], v[22:23]
	v_pk_fma_f32 v[20:21], v[0:1], v[24:25], v[20:21]
	v_cvt_pk_bf16_f32 v24, v34, v35
	v_cvt_pk_bf16_f32 v25, v28, v29
	v_cvt_pk_bf16_f32 v20, v20, v21
	v_cvt_pk_bf16_f32 v21, v22, v23
	global_store_dwordx2 v[32:33], v[24:25], off offset:1024
	global_store_dwordx2 v[32:33], v[20:21], off offset:1088
	s_cbranch_execz .LBB0_861
